# P5b loop VALU in packed f32 form (v_pk_mul_f32 / v_pk_fma_f32): half the VALU instructions, same per-element arithmetic
# baseline (speedup 1.0000x reference)
; __device__ __forceinline__ unsigned pk2(float lo, float hi) { return pg8::cvt_pk_bf16(lo, hi); }
; __device__ __forceinline__ float bf_lo(unsigned w) { return __uint_as_float(w << 16); }
; __device__ __forceinline__ float bf_hi(unsigned w) { return __uint_as_float(w & 0xffff0000u); }
; #define INP(i) ((const float*)(const GAS float*)KARG(8 * (i)))
; #define X_IN INP(0)
; #define P_IN INP(1)
; __global__ void __launch_bounds__(512, 2) fwd(Params P) {
;     ...
;     if (PHASE_MASK & (1 << 6)) {
;         const f32x4* g1 = (const f32x4*)INP(12) + lane; const f32x4* g2 = (const f32x4*)INP(13) + lane;
;         for (int m = gw; m < T_TOK; m += NGW) {
;             const float rsy = __builtin_amdgcn_rsqf(ssq_y[m] * (1.f / DM) + EPS);
;             const f32x4* xr = (const f32x4*)(X_IN + (size_t)m * DM) + lane; const u32x2* yr = (const u32x2*)(YB + (size_t)m * DM) + lane;
;             f32x4* orow = (f32x4*)(OUT_P + (size_t)m * DM) + lane;
;             f32x4 v[8]; float s = 0.f;
; #pragma unroll
;             for (int j = 0; j < 8; ++j) { const f32x4 xv = __builtin_nontemporal_load(&xr[64 * j]); const u32x2 yw = __builtin_nontemporal_load(&yr[64 * j]); const f32x4 g = g1[64 * j];
;                 f32x4 t; t.x = xv.x + bf_lo(yw.x) * rsy * g.x; t.y = xv.y + bf_hi(yw.x) * rsy * g.y; t.z = xv.z + bf_lo(yw.y) * rsy * g.z; t.w = xv.w + bf_hi(yw.y) * rsy * g.w;
;                 v[j] = t; __builtin_nontemporal_store(t, &orow[64 * j]); s += (t.x * t.x + t.y * t.y) + (t.z * t.z + t.w * t.w); }
;             const float rs = __builtin_amdgcn_rsqf(wave_sum(s) * (1.f / DM) + EPS);
;             u32x2* o = (u32x2*)(XN + (size_t)m * DM) + lane;
; #pragma unroll
;             for (int j = 0; j < 8; ++j) { const f32x4 g = g2[64 * j]; u32x2 w; w.x = pk2(v[j].x * rs * g.x, v[j].y * rs * g.y); w.y = pk2(v[j].z * rs * g.z, v[j].w * rs * g.w); o[64 * j] = w; }
;             const f32x4 pv = ((const f32x4*)(P_IN + (size_t)m * PLE))[lane]; u32x2 pw; pw.x = pk2(pv.x, pv.y); pw.y = pk2(pv.z, pv.w);
;             ((u32x2*)(PB + (size_t)m * PLE))[lane] = pw;
.LBB0_1226:
	s_or_b64 exec, exec, s[6:7]
	v_readlane_b32 s12, v246, 4
	v_readlane_b32 s13, v246, 5
	s_mov_b64 s[8:9], s[0:1]
	s_mov_b64 s[10:11], s[0:1]
	s_waitcnt lgkmcnt(0)
	v_cndmask_b32_e64 v0, 0, 1, s[12:13]
	v_cmp_ne_u32_e64 s[6:7], 1, v0
	s_andn2_b64 vcc, exec, s[12:13]
	s_barrier
	s_cbranch_vccnz .LBB0_1229
	s_load_dwordx2 s[8:9], s[0:1], 0x0
	s_load_dwordx2 s[10:11], s[0:1], 0xa8
	s_load_dwordx2 s[18:19], s[0:1], 0xa0
	s_load_dwordx2 s[20:21], s[0:1], 0x8
	s_load_dwordx2 s[24:25], s[0:1], 0x60
	s_load_dwordx2 s[26:27], s[0:1], 0x68
	v_mov_b32_e32 v167, 0
	v_lshlrev_b32_e32 v181, 3, v179
	v_mov_b32_e32 v182, 0x358637bd
	s_mov_b32 s30, s80
	s_waitcnt lgkmcnt(0)
	s_add_u32 s8, s8, 0x1000
	s_addc_u32 s9, s9, 0
	s_add_u32 s18, s18, 0x1000
	s_addc_u32 s19, s19, 0
	s_add_u32 s12, s10, 0x40000
	s_addc_u32 s13, s11, 0
	s_add_u32 s14, s10, 0x18000000
	s_addc_u32 s15, s11, 0
	s_add_u32 s16, s10, 0x8000000
	s_addc_u32 s17, s11, 0
	s_add_u32 s22, s10, 0x30000000
	s_addc_u32 s23, s11, 0
	s_add_u32 s28, s24, 0x1000
	s_addc_u32 s29, s25, 0
	s_add_u32 s34, s26, 0x1000
	s_addc_u32 s35, s27, 0
	global_load_dwordx4 v[0:3], v166, s[24:25] offset:0
	global_load_dwordx4 v[4:7], v166, s[24:25] offset:1024
	global_load_dwordx4 v[8:11], v166, s[24:25] offset:2048
	global_load_dwordx4 v[12:15], v166, s[24:25] offset:3072
	global_load_dwordx4 v[16:19], v166, s[28:29] offset:0
	global_load_dwordx4 v[20:23], v166, s[28:29] offset:1024
	global_load_dwordx4 v[24:27], v166, s[28:29] offset:2048
	global_load_dwordx4 v[28:31], v166, s[28:29] offset:3072
	global_load_dwordx4 v[32:35], v166, s[26:27] offset:0
	global_load_dwordx4 v[36:39], v166, s[26:27] offset:1024
	global_load_dwordx4 v[40:43], v166, s[26:27] offset:2048
	global_load_dwordx4 v[44:47], v166, s[26:27] offset:3072
	global_load_dwordx4 v[48:51], v166, s[34:35] offset:0
	global_load_dwordx4 v[52:55], v166, s[34:35] offset:1024
	global_load_dwordx4 v[56:59], v166, s[34:35] offset:2048
	global_load_dwordx4 v[60:63], v166, s[34:35] offset:3072
	s_lshl_b32 s2, s30, 13
	s_add_u32 s24, s8, s2
	s_addc_u32 s25, s9, 0
	s_lshl_b32 s2, s30, 12
	s_add_u32 s26, s14, s2
	s_addc_u32 s27, s15, 0
	s_lshl_b32 s2, s30, 2
	s_add_u32 s28, s12, s2
	s_addc_u32 s29, s13, 0
	s_lshl_b32 s2, s30, 10
	s_add_u32 s34, s20, s2
	s_addc_u32 s35, s21, 0
	global_load_dword v112, v167, s[28:29]
	global_load_dwordx4 v[64:67], v166, s[24:25] offset:-4096 nt
	global_load_dwordx2 v[96:97], v181, s[26:27] offset:0 nt
	global_load_dwordx4 v[68:71], v166, s[24:25] offset:-3072 nt
	global_load_dwordx2 v[98:99], v181, s[26:27] offset:512 nt
	global_load_dwordx4 v[72:75], v166, s[24:25] offset:-2048 nt
	global_load_dwordx2 v[100:101], v181, s[26:27] offset:1024 nt
	global_load_dwordx4 v[76:79], v166, s[24:25] offset:-1024 nt
	global_load_dwordx2 v[102:103], v181, s[26:27] offset:1536 nt
	global_load_dwordx4 v[80:83], v166, s[24:25] offset:0 nt
	global_load_dwordx2 v[104:105], v181, s[26:27] offset:2048 nt
	global_load_dwordx4 v[84:87], v166, s[24:25] offset:1024 nt
	global_load_dwordx2 v[106:107], v181, s[26:27] offset:2560 nt
	global_load_dwordx4 v[88:91], v166, s[24:25] offset:2048 nt
	global_load_dwordx2 v[108:109], v181, s[26:27] offset:3072 nt
	global_load_dwordx4 v[92:95], v166, s[24:25] offset:3072 nt
	global_load_dwordx2 v[110:111], v181, s[26:27] offset:3584 nt
	global_load_dwordx4 v[114:117], v166, s[34:35]
	s_lshl_b32 s2, s30, 13
	s_add_u32 s36, s18, s2
	s_addc_u32 s37, s19, 0
	s_lshl_b32 s2, s30, 12
	s_add_u32 s38, s16, s2
	s_addc_u32 s39, s17, 0
	s_lshl_b32 s2, s30, 9
	s_add_u32 s40, s22, s2
	s_addc_u32 s41, s23, 0
	s_add_i32 s10, s30, s82
	s_cmpk_gt_i32 s10, 0x7fff
	s_cbranch_scc1 .Lp5b_tail_a
	s_lshl_b32 s2, s10, 13
	s_add_u32 s24, s8, s2
	s_addc_u32 s25, s9, 0
	s_lshl_b32 s2, s10, 12
	s_add_u32 s26, s14, s2
	s_addc_u32 s27, s15, 0
	s_lshl_b32 s2, s10, 2
	s_add_u32 s28, s12, s2
	s_addc_u32 s29, s13, 0
	s_lshl_b32 s2, s10, 10
	s_add_u32 s34, s20, s2
	s_addc_u32 s35, s21, 0
	global_load_dword v168, v167, s[28:29]
	global_load_dwordx4 v[118:121], v166, s[24:25] offset:-4096 nt
	global_load_dwordx2 v[150:151], v181, s[26:27] offset:0 nt
	global_load_dwordx4 v[122:125], v166, s[24:25] offset:-3072 nt
	global_load_dwordx2 v[152:153], v181, s[26:27] offset:512 nt
	global_load_dwordx4 v[126:129], v166, s[24:25] offset:-2048 nt
	global_load_dwordx2 v[154:155], v181, s[26:27] offset:1024 nt
	global_load_dwordx4 v[130:133], v166, s[24:25] offset:-1024 nt
	global_load_dwordx2 v[156:157], v181, s[26:27] offset:1536 nt
	global_load_dwordx4 v[134:137], v166, s[24:25] offset:0 nt
	global_load_dwordx2 v[158:159], v181, s[26:27] offset:2048 nt
	global_load_dwordx4 v[138:141], v166, s[24:25] offset:1024 nt
	global_load_dwordx2 v[160:161], v181, s[26:27] offset:2560 nt
	global_load_dwordx4 v[142:145], v166, s[24:25] offset:2048 nt
	global_load_dwordx2 v[162:163], v181, s[26:27] offset:3072 nt
	global_load_dwordx4 v[146:149], v166, s[24:25] offset:3072 nt
	global_load_dwordx2 v[164:165], v181, s[26:27] offset:3584 nt
	global_load_dwordx4 v[170:173], v166, s[34:35]
	s_waitcnt vmcnt(33)
	v_fmamk_f32 v184, v112, 0x3a000000, v182
	v_rsq_f32_e32 v184, v184
	v_lshlrev_b32_e32 v174, 16, v96
	v_and_b32_e32 v175, 0xffff0000, v96
	v_lshlrev_b32_e32 v176, 16, v97
	v_and_b32_e32 v177, 0xffff0000, v97
	v_pk_mul_f32 v[174:175], v[184:185], v[174:175] op_sel_hi:[0,1]
	v_pk_mul_f32 v[176:177], v[184:185], v[176:177] op_sel_hi:[0,1]
	v_pk_fma_f32 v[64:65], v[0:1], v[174:175], v[64:65]
	v_pk_fma_f32 v[66:67], v[2:3], v[176:177], v[66:67]
	global_store_dwordx4 v166, v[64:67], s[36:37] offset:-4096 nt
	v_pk_mul_f32 v[186:187], v[64:65], v[64:65]
	v_pk_mul_f32 v[188:189], v[66:67], v[66:67]
	s_waitcnt vmcnt(32)
	v_lshlrev_b32_e32 v174, 16, v98
	v_and_b32_e32 v175, 0xffff0000, v98
	v_lshlrev_b32_e32 v176, 16, v99
	v_and_b32_e32 v177, 0xffff0000, v99
	v_pk_mul_f32 v[174:175], v[184:185], v[174:175] op_sel_hi:[0,1]
	v_pk_mul_f32 v[176:177], v[184:185], v[176:177] op_sel_hi:[0,1]
	v_pk_fma_f32 v[68:69], v[4:5], v[174:175], v[68:69]
	v_pk_fma_f32 v[70:71], v[6:7], v[176:177], v[70:71]
	global_store_dwordx4 v166, v[68:71], s[36:37] offset:-3072 nt
	v_pk_fma_f32 v[186:187], v[68:69], v[68:69], v[186:187]
	v_pk_fma_f32 v[188:189], v[70:71], v[70:71], v[188:189]
	s_waitcnt vmcnt(31)
	v_lshlrev_b32_e32 v174, 16, v100
	v_and_b32_e32 v175, 0xffff0000, v100
	v_lshlrev_b32_e32 v176, 16, v101
	v_and_b32_e32 v177, 0xffff0000, v101
	v_pk_mul_f32 v[174:175], v[184:185], v[174:175] op_sel_hi:[0,1]
	v_pk_mul_f32 v[176:177], v[184:185], v[176:177] op_sel_hi:[0,1]
	v_pk_fma_f32 v[72:73], v[8:9], v[174:175], v[72:73]
	v_pk_fma_f32 v[74:75], v[10:11], v[176:177], v[74:75]
	global_store_dwordx4 v166, v[72:75], s[36:37] offset:-2048 nt
	v_pk_fma_f32 v[186:187], v[72:73], v[72:73], v[186:187]
	v_pk_fma_f32 v[188:189], v[74:75], v[74:75], v[188:189]
	s_waitcnt vmcnt(30)
	v_lshlrev_b32_e32 v174, 16, v102
	v_and_b32_e32 v175, 0xffff0000, v102
	v_lshlrev_b32_e32 v176, 16, v103
	v_and_b32_e32 v177, 0xffff0000, v103
	v_pk_mul_f32 v[174:175], v[184:185], v[174:175] op_sel_hi:[0,1]
	v_pk_mul_f32 v[176:177], v[184:185], v[176:177] op_sel_hi:[0,1]
	v_pk_fma_f32 v[76:77], v[12:13], v[174:175], v[76:77]
	v_pk_fma_f32 v[78:79], v[14:15], v[176:177], v[78:79]
	global_store_dwordx4 v166, v[76:79], s[36:37] offset:-1024 nt
	v_pk_fma_f32 v[186:187], v[76:77], v[76:77], v[186:187]
	v_pk_fma_f32 v[188:189], v[78:79], v[78:79], v[188:189]
	s_waitcnt vmcnt(29)
	v_lshlrev_b32_e32 v174, 16, v104
	v_and_b32_e32 v175, 0xffff0000, v104
	v_lshlrev_b32_e32 v176, 16, v105
	v_and_b32_e32 v177, 0xffff0000, v105
	v_pk_mul_f32 v[174:175], v[184:185], v[174:175] op_sel_hi:[0,1]
	v_pk_mul_f32 v[176:177], v[184:185], v[176:177] op_sel_hi:[0,1]
	v_pk_fma_f32 v[80:81], v[16:17], v[174:175], v[80:81]
	v_pk_fma_f32 v[82:83], v[18:19], v[176:177], v[82:83]
	global_store_dwordx4 v166, v[80:83], s[36:37] offset:0 nt
	v_pk_fma_f32 v[186:187], v[80:81], v[80:81], v[186:187]
	v_pk_fma_f32 v[188:189], v[82:83], v[82:83], v[188:189]
	s_waitcnt vmcnt(28)
	v_lshlrev_b32_e32 v174, 16, v106
	v_and_b32_e32 v175, 0xffff0000, v106
	v_lshlrev_b32_e32 v176, 16, v107
	v_and_b32_e32 v177, 0xffff0000, v107
	v_pk_mul_f32 v[174:175], v[184:185], v[174:175] op_sel_hi:[0,1]
	v_pk_mul_f32 v[176:177], v[184:185], v[176:177] op_sel_hi:[0,1]
	v_pk_fma_f32 v[84:85], v[20:21], v[174:175], v[84:85]
	v_pk_fma_f32 v[86:87], v[22:23], v[176:177], v[86:87]
	global_store_dwordx4 v166, v[84:87], s[36:37] offset:1024 nt
	v_pk_fma_f32 v[186:187], v[84:85], v[84:85], v[186:187]
	v_pk_fma_f32 v[188:189], v[86:87], v[86:87], v[188:189]
	s_waitcnt vmcnt(27)
	v_lshlrev_b32_e32 v174, 16, v108
	v_and_b32_e32 v175, 0xffff0000, v108
	v_lshlrev_b32_e32 v176, 16, v109
	v_and_b32_e32 v177, 0xffff0000, v109
	v_pk_mul_f32 v[174:175], v[184:185], v[174:175] op_sel_hi:[0,1]
	v_pk_mul_f32 v[176:177], v[184:185], v[176:177] op_sel_hi:[0,1]
	v_pk_fma_f32 v[88:89], v[24:25], v[174:175], v[88:89]
	v_pk_fma_f32 v[90:91], v[26:27], v[176:177], v[90:91]
	global_store_dwordx4 v166, v[88:91], s[36:37] offset:2048 nt
	v_pk_fma_f32 v[186:187], v[88:89], v[88:89], v[186:187]
	v_pk_fma_f32 v[188:189], v[90:91], v[90:91], v[188:189]
	s_waitcnt vmcnt(26)
	v_lshlrev_b32_e32 v174, 16, v110
	v_and_b32_e32 v175, 0xffff0000, v110
	v_lshlrev_b32_e32 v176, 16, v111
	v_and_b32_e32 v177, 0xffff0000, v111
	v_pk_mul_f32 v[174:175], v[184:185], v[174:175] op_sel_hi:[0,1]
	v_pk_mul_f32 v[176:177], v[184:185], v[176:177] op_sel_hi:[0,1]
	v_pk_fma_f32 v[92:93], v[28:29], v[174:175], v[92:93]
	v_pk_fma_f32 v[94:95], v[30:31], v[176:177], v[94:95]
	global_store_dwordx4 v166, v[92:95], s[36:37] offset:3072 nt
	v_pk_fma_f32 v[186:187], v[92:93], v[92:93], v[186:187]
	v_pk_fma_f32 v[188:189], v[94:95], v[94:95], v[188:189]
	v_add_f32_e32 v186, v186, v187
	v_add_f32_e32 v188, v188, v189
	v_add_f32_e32 v186, v186, v188
	s_nop 1
	v_add_f32_dpp v186, v186, v186 quad_perm:[1,0,3,2] row_mask:0xf bank_mask:0xf
	s_nop 1
	v_add_f32_dpp v186, v186, v186 quad_perm:[2,3,0,1] row_mask:0xf bank_mask:0xf
	s_nop 1
	v_add_f32_dpp v186, v186, v186 row_half_mirror row_mask:0xf bank_mask:0xf
	s_nop 1
	v_add_f32_dpp v186, v186, v186 row_mirror row_mask:0xf bank_mask:0xf
	s_nop 1
	v_readlane_b32 s24, v186, 0
	v_readlane_b32 s25, v186, 16
	v_readlane_b32 s26, v186, 32
	v_readlane_b32 s27, v186, 48
	v_mov_b32_e32 v190, s24
	v_add_f32_e32 v190, s25, v190
	v_add_f32_e32 v190, s26, v190
	v_add_f32_e32 v190, s27, v190
	v_fmamk_f32 v190, v190, 0x3a000000, v182
	v_rsq_f32_e32 v190, v190
	s_nop 0
	v_pk_mul_f32 v[174:175], v[190:191], v[64:65] op_sel_hi:[0,1]
	v_pk_mul_f32 v[176:177], v[190:191], v[66:67] op_sel_hi:[0,1]
	v_pk_mul_f32 v[174:175], v[174:175], v[32:33]
	v_pk_mul_f32 v[176:177], v[176:177], v[34:35]
	v_cvt_pk_bf16_f32 v96, v174, v175
	v_cvt_pk_bf16_f32 v97, v176, v177
	global_store_dwordx2 v181, v[96:97], s[38:39] offset:0
	v_pk_mul_f32 v[174:175], v[190:191], v[68:69] op_sel_hi:[0,1]
	v_pk_mul_f32 v[176:177], v[190:191], v[70:71] op_sel_hi:[0,1]
	v_pk_mul_f32 v[174:175], v[174:175], v[36:37]
	v_pk_mul_f32 v[176:177], v[176:177], v[38:39]
	v_cvt_pk_bf16_f32 v98, v174, v175
	v_cvt_pk_bf16_f32 v99, v176, v177
	global_store_dwordx2 v181, v[98:99], s[38:39] offset:512
	v_pk_mul_f32 v[174:175], v[190:191], v[72:73] op_sel_hi:[0,1]
	v_pk_mul_f32 v[176:177], v[190:191], v[74:75] op_sel_hi:[0,1]
	v_pk_mul_f32 v[174:175], v[174:175], v[40:41]
	v_pk_mul_f32 v[176:177], v[176:177], v[42:43]
	v_cvt_pk_bf16_f32 v100, v174, v175
	v_cvt_pk_bf16_f32 v101, v176, v177
	global_store_dwordx2 v181, v[100:101], s[38:39] offset:1024
	v_pk_mul_f32 v[174:175], v[190:191], v[76:77] op_sel_hi:[0,1]
	v_pk_mul_f32 v[176:177], v[190:191], v[78:79] op_sel_hi:[0,1]
	v_pk_mul_f32 v[174:175], v[174:175], v[44:45]
	v_pk_mul_f32 v[176:177], v[176:177], v[46:47]
	v_cvt_pk_bf16_f32 v102, v174, v175
	v_cvt_pk_bf16_f32 v103, v176, v177
	global_store_dwordx2 v181, v[102:103], s[38:39] offset:1536
	v_pk_mul_f32 v[174:175], v[190:191], v[80:81] op_sel_hi:[0,1]
	v_pk_mul_f32 v[176:177], v[190:191], v[82:83] op_sel_hi:[0,1]
	v_pk_mul_f32 v[174:175], v[174:175], v[48:49]
	v_pk_mul_f32 v[176:177], v[176:177], v[50:51]
	v_cvt_pk_bf16_f32 v104, v174, v175
	v_cvt_pk_bf16_f32 v105, v176, v177
	global_store_dwordx2 v181, v[104:105], s[38:39] offset:2048
	v_pk_mul_f32 v[174:175], v[190:191], v[84:85] op_sel_hi:[0,1]
	v_pk_mul_f32 v[176:177], v[190:191], v[86:87] op_sel_hi:[0,1]
	v_pk_mul_f32 v[174:175], v[174:175], v[52:53]
	v_pk_mul_f32 v[176:177], v[176:177], v[54:55]
	v_cvt_pk_bf16_f32 v106, v174, v175
	v_cvt_pk_bf16_f32 v107, v176, v177
	global_store_dwordx2 v181, v[106:107], s[38:39] offset:2560
	v_pk_mul_f32 v[174:175], v[190:191], v[88:89] op_sel_hi:[0,1]
	v_pk_mul_f32 v[176:177], v[190:191], v[90:91] op_sel_hi:[0,1]
	v_pk_mul_f32 v[174:175], v[174:175], v[56:57]
	v_pk_mul_f32 v[176:177], v[176:177], v[58:59]
	v_cvt_pk_bf16_f32 v108, v174, v175
	v_cvt_pk_bf16_f32 v109, v176, v177
	global_store_dwordx2 v181, v[108:109], s[38:39] offset:3072
	v_pk_mul_f32 v[174:175], v[190:191], v[92:93] op_sel_hi:[0,1]
	v_pk_mul_f32 v[176:177], v[190:191], v[94:95] op_sel_hi:[0,1]
	v_pk_mul_f32 v[174:175], v[174:175], v[60:61]
	v_pk_mul_f32 v[176:177], v[176:177], v[62:63]
	v_cvt_pk_bf16_f32 v110, v174, v175
	v_cvt_pk_bf16_f32 v111, v176, v177
	global_store_dwordx2 v181, v[110:111], s[38:39] offset:3584
	s_waitcnt vmcnt(34)
	v_cvt_pk_bf16_f32 v114, v114, v115
	v_cvt_pk_bf16_f32 v115, v116, v117
	global_store_dwordx2 v181, v[114:115], s[40:41]
	s_mov_b32 s30, s10
.Lp5b_loop:
	s_lshl_b32 s2, s30, 13
	s_add_u32 s36, s18, s2
	s_addc_u32 s37, s19, 0
	s_lshl_b32 s2, s30, 12
	s_add_u32 s38, s16, s2
	s_addc_u32 s39, s17, 0
	s_lshl_b32 s2, s30, 9
	s_add_u32 s40, s22, s2
	s_addc_u32 s41, s23, 0
	s_add_i32 s10, s30, s82
	s_cmpk_gt_i32 s10, 0x7fff
	s_cbranch_scc1 .Lp5b_tail_b
	s_lshl_b32 s2, s10, 13
	s_add_u32 s24, s8, s2
	s_addc_u32 s25, s9, 0
	s_lshl_b32 s2, s10, 12
	s_add_u32 s26, s14, s2
	s_addc_u32 s27, s15, 0
	s_lshl_b32 s2, s10, 2
	s_add_u32 s28, s12, s2
	s_addc_u32 s29, s13, 0
	s_lshl_b32 s2, s10, 10
	s_add_u32 s34, s20, s2
	s_addc_u32 s35, s21, 0
	global_load_dword v112, v167, s[28:29]
	global_load_dwordx4 v[64:67], v166, s[24:25] offset:-4096 nt
	global_load_dwordx2 v[96:97], v181, s[26:27] offset:0 nt
	global_load_dwordx4 v[68:71], v166, s[24:25] offset:-3072 nt
	global_load_dwordx2 v[98:99], v181, s[26:27] offset:512 nt
	global_load_dwordx4 v[72:75], v166, s[24:25] offset:-2048 nt
	global_load_dwordx2 v[100:101], v181, s[26:27] offset:1024 nt
	global_load_dwordx4 v[76:79], v166, s[24:25] offset:-1024 nt
	global_load_dwordx2 v[102:103], v181, s[26:27] offset:1536 nt
	global_load_dwordx4 v[80:83], v166, s[24:25] offset:0 nt
	global_load_dwordx2 v[104:105], v181, s[26:27] offset:2048 nt
	global_load_dwordx4 v[84:87], v166, s[24:25] offset:1024 nt
	global_load_dwordx2 v[106:107], v181, s[26:27] offset:2560 nt
	global_load_dwordx4 v[88:91], v166, s[24:25] offset:2048 nt
	global_load_dwordx2 v[108:109], v181, s[26:27] offset:3072 nt
	global_load_dwordx4 v[92:95], v166, s[24:25] offset:3072 nt
	global_load_dwordx2 v[110:111], v181, s[26:27] offset:3584 nt
	global_load_dwordx4 v[114:117], v166, s[34:35]
	s_waitcnt vmcnt(50)
	v_fmamk_f32 v184, v168, 0x3a000000, v182
	v_rsq_f32_e32 v184, v184
	v_lshlrev_b32_e32 v174, 16, v150
	v_and_b32_e32 v175, 0xffff0000, v150
	v_lshlrev_b32_e32 v176, 16, v151
	v_and_b32_e32 v177, 0xffff0000, v151
	v_pk_mul_f32 v[174:175], v[184:185], v[174:175] op_sel_hi:[0,1]
	v_pk_mul_f32 v[176:177], v[184:185], v[176:177] op_sel_hi:[0,1]
	v_pk_fma_f32 v[118:119], v[0:1], v[174:175], v[118:119]
	v_pk_fma_f32 v[120:121], v[2:3], v[176:177], v[120:121]
	global_store_dwordx4 v166, v[118:121], s[36:37] offset:-4096 nt
	v_pk_mul_f32 v[186:187], v[118:119], v[118:119]
	v_pk_mul_f32 v[188:189], v[120:121], v[120:121]
	s_waitcnt vmcnt(49)
	v_lshlrev_b32_e32 v174, 16, v152
	v_and_b32_e32 v175, 0xffff0000, v152
	v_lshlrev_b32_e32 v176, 16, v153
	v_and_b32_e32 v177, 0xffff0000, v153
	v_pk_mul_f32 v[174:175], v[184:185], v[174:175] op_sel_hi:[0,1]
	v_pk_mul_f32 v[176:177], v[184:185], v[176:177] op_sel_hi:[0,1]
	v_pk_fma_f32 v[122:123], v[4:5], v[174:175], v[122:123]
	v_pk_fma_f32 v[124:125], v[6:7], v[176:177], v[124:125]
	global_store_dwordx4 v166, v[122:125], s[36:37] offset:-3072 nt
	v_pk_fma_f32 v[186:187], v[122:123], v[122:123], v[186:187]
	v_pk_fma_f32 v[188:189], v[124:125], v[124:125], v[188:189]
	s_waitcnt vmcnt(48)
	v_lshlrev_b32_e32 v174, 16, v154
	v_and_b32_e32 v175, 0xffff0000, v154
	v_lshlrev_b32_e32 v176, 16, v155
	v_and_b32_e32 v177, 0xffff0000, v155
	v_pk_mul_f32 v[174:175], v[184:185], v[174:175] op_sel_hi:[0,1]
	v_pk_mul_f32 v[176:177], v[184:185], v[176:177] op_sel_hi:[0,1]
	v_pk_fma_f32 v[126:127], v[8:9], v[174:175], v[126:127]
	v_pk_fma_f32 v[128:129], v[10:11], v[176:177], v[128:129]
	global_store_dwordx4 v166, v[126:129], s[36:37] offset:-2048 nt
	v_pk_fma_f32 v[186:187], v[126:127], v[126:127], v[186:187]
	v_pk_fma_f32 v[188:189], v[128:129], v[128:129], v[188:189]
	s_waitcnt vmcnt(47)
	v_lshlrev_b32_e32 v174, 16, v156
	v_and_b32_e32 v175, 0xffff0000, v156
	v_lshlrev_b32_e32 v176, 16, v157
	v_and_b32_e32 v177, 0xffff0000, v157
	v_pk_mul_f32 v[174:175], v[184:185], v[174:175] op_sel_hi:[0,1]
	v_pk_mul_f32 v[176:177], v[184:185], v[176:177] op_sel_hi:[0,1]
	v_pk_fma_f32 v[130:131], v[12:13], v[174:175], v[130:131]
	v_pk_fma_f32 v[132:133], v[14:15], v[176:177], v[132:133]
	global_store_dwordx4 v166, v[130:133], s[36:37] offset:-1024 nt
	v_pk_fma_f32 v[186:187], v[130:131], v[130:131], v[186:187]
	v_pk_fma_f32 v[188:189], v[132:133], v[132:133], v[188:189]
	s_waitcnt vmcnt(46)
	v_lshlrev_b32_e32 v174, 16, v158
	v_and_b32_e32 v175, 0xffff0000, v158
	v_lshlrev_b32_e32 v176, 16, v159
	v_and_b32_e32 v177, 0xffff0000, v159
	v_pk_mul_f32 v[174:175], v[184:185], v[174:175] op_sel_hi:[0,1]
	v_pk_mul_f32 v[176:177], v[184:185], v[176:177] op_sel_hi:[0,1]
	v_pk_fma_f32 v[134:135], v[16:17], v[174:175], v[134:135]
	v_pk_fma_f32 v[136:137], v[18:19], v[176:177], v[136:137]
	global_store_dwordx4 v166, v[134:137], s[36:37] offset:0 nt
	v_pk_fma_f32 v[186:187], v[134:135], v[134:135], v[186:187]
	v_pk_fma_f32 v[188:189], v[136:137], v[136:137], v[188:189]
	s_waitcnt vmcnt(45)
	v_lshlrev_b32_e32 v174, 16, v160
	v_and_b32_e32 v175, 0xffff0000, v160
	v_lshlrev_b32_e32 v176, 16, v161
	v_and_b32_e32 v177, 0xffff0000, v161
	v_pk_mul_f32 v[174:175], v[184:185], v[174:175] op_sel_hi:[0,1]
	v_pk_mul_f32 v[176:177], v[184:185], v[176:177] op_sel_hi:[0,1]
	v_pk_fma_f32 v[138:139], v[20:21], v[174:175], v[138:139]
	v_pk_fma_f32 v[140:141], v[22:23], v[176:177], v[140:141]
	global_store_dwordx4 v166, v[138:141], s[36:37] offset:1024 nt
	v_pk_fma_f32 v[186:187], v[138:139], v[138:139], v[186:187]
	v_pk_fma_f32 v[188:189], v[140:141], v[140:141], v[188:189]
	s_waitcnt vmcnt(44)
	v_lshlrev_b32_e32 v174, 16, v162
	v_and_b32_e32 v175, 0xffff0000, v162
	v_lshlrev_b32_e32 v176, 16, v163
	v_and_b32_e32 v177, 0xffff0000, v163
	v_pk_mul_f32 v[174:175], v[184:185], v[174:175] op_sel_hi:[0,1]
	v_pk_mul_f32 v[176:177], v[184:185], v[176:177] op_sel_hi:[0,1]
	v_pk_fma_f32 v[142:143], v[24:25], v[174:175], v[142:143]
	v_pk_fma_f32 v[144:145], v[26:27], v[176:177], v[144:145]
	global_store_dwordx4 v166, v[142:145], s[36:37] offset:2048 nt
	v_pk_fma_f32 v[186:187], v[142:143], v[142:143], v[186:187]
	v_pk_fma_f32 v[188:189], v[144:145], v[144:145], v[188:189]
	s_waitcnt vmcnt(43)
	v_lshlrev_b32_e32 v174, 16, v164
	v_and_b32_e32 v175, 0xffff0000, v164
	v_lshlrev_b32_e32 v176, 16, v165
	v_and_b32_e32 v177, 0xffff0000, v165
	v_pk_mul_f32 v[174:175], v[184:185], v[174:175] op_sel_hi:[0,1]
	v_pk_mul_f32 v[176:177], v[184:185], v[176:177] op_sel_hi:[0,1]
	v_pk_fma_f32 v[146:147], v[28:29], v[174:175], v[146:147]
	v_pk_fma_f32 v[148:149], v[30:31], v[176:177], v[148:149]
	global_store_dwordx4 v166, v[146:149], s[36:37] offset:3072 nt
	v_pk_fma_f32 v[186:187], v[146:147], v[146:147], v[186:187]
	v_pk_fma_f32 v[188:189], v[148:149], v[148:149], v[188:189]
	v_add_f32_e32 v186, v186, v187
	v_add_f32_e32 v188, v188, v189
	v_add_f32_e32 v186, v186, v188
	s_nop 1
	v_add_f32_dpp v186, v186, v186 quad_perm:[1,0,3,2] row_mask:0xf bank_mask:0xf
	s_nop 1
	v_add_f32_dpp v186, v186, v186 quad_perm:[2,3,0,1] row_mask:0xf bank_mask:0xf
	s_nop 1
	v_add_f32_dpp v186, v186, v186 row_half_mirror row_mask:0xf bank_mask:0xf
	s_nop 1
	v_add_f32_dpp v186, v186, v186 row_mirror row_mask:0xf bank_mask:0xf
	s_nop 1
	v_readlane_b32 s24, v186, 0
	v_readlane_b32 s25, v186, 16
	v_readlane_b32 s26, v186, 32
	v_readlane_b32 s27, v186, 48
	v_mov_b32_e32 v190, s24
	v_add_f32_e32 v190, s25, v190
	v_add_f32_e32 v190, s26, v190
	v_add_f32_e32 v190, s27, v190
	v_fmamk_f32 v190, v190, 0x3a000000, v182
	v_rsq_f32_e32 v190, v190
	s_nop 0
	v_pk_mul_f32 v[174:175], v[190:191], v[118:119] op_sel_hi:[0,1]
	v_pk_mul_f32 v[176:177], v[190:191], v[120:121] op_sel_hi:[0,1]
	v_pk_mul_f32 v[174:175], v[174:175], v[32:33]
	v_pk_mul_f32 v[176:177], v[176:177], v[34:35]
	v_cvt_pk_bf16_f32 v150, v174, v175
	v_cvt_pk_bf16_f32 v151, v176, v177
	global_store_dwordx2 v181, v[150:151], s[38:39] offset:0
	v_pk_mul_f32 v[174:175], v[190:191], v[122:123] op_sel_hi:[0,1]
	v_pk_mul_f32 v[176:177], v[190:191], v[124:125] op_sel_hi:[0,1]
	v_pk_mul_f32 v[174:175], v[174:175], v[36:37]
	v_pk_mul_f32 v[176:177], v[176:177], v[38:39]
	v_cvt_pk_bf16_f32 v152, v174, v175
	v_cvt_pk_bf16_f32 v153, v176, v177
	global_store_dwordx2 v181, v[152:153], s[38:39] offset:512
	v_pk_mul_f32 v[174:175], v[190:191], v[126:127] op_sel_hi:[0,1]
	v_pk_mul_f32 v[176:177], v[190:191], v[128:129] op_sel_hi:[0,1]
	v_pk_mul_f32 v[174:175], v[174:175], v[40:41]
	v_pk_mul_f32 v[176:177], v[176:177], v[42:43]
	v_cvt_pk_bf16_f32 v154, v174, v175
	v_cvt_pk_bf16_f32 v155, v176, v177
	global_store_dwordx2 v181, v[154:155], s[38:39] offset:1024
	v_pk_mul_f32 v[174:175], v[190:191], v[130:131] op_sel_hi:[0,1]
	v_pk_mul_f32 v[176:177], v[190:191], v[132:133] op_sel_hi:[0,1]
	v_pk_mul_f32 v[174:175], v[174:175], v[44:45]
	v_pk_mul_f32 v[176:177], v[176:177], v[46:47]
	v_cvt_pk_bf16_f32 v156, v174, v175
	v_cvt_pk_bf16_f32 v157, v176, v177
	global_store_dwordx2 v181, v[156:157], s[38:39] offset:1536
	v_pk_mul_f32 v[174:175], v[190:191], v[134:135] op_sel_hi:[0,1]
	v_pk_mul_f32 v[176:177], v[190:191], v[136:137] op_sel_hi:[0,1]
	v_pk_mul_f32 v[174:175], v[174:175], v[48:49]
	v_pk_mul_f32 v[176:177], v[176:177], v[50:51]
	v_cvt_pk_bf16_f32 v158, v174, v175
	v_cvt_pk_bf16_f32 v159, v176, v177
	global_store_dwordx2 v181, v[158:159], s[38:39] offset:2048
	v_pk_mul_f32 v[174:175], v[190:191], v[138:139] op_sel_hi:[0,1]
	v_pk_mul_f32 v[176:177], v[190:191], v[140:141] op_sel_hi:[0,1]
	v_pk_mul_f32 v[174:175], v[174:175], v[52:53]
	v_pk_mul_f32 v[176:177], v[176:177], v[54:55]
	v_cvt_pk_bf16_f32 v160, v174, v175
	v_cvt_pk_bf16_f32 v161, v176, v177
	global_store_dwordx2 v181, v[160:161], s[38:39] offset:2560
	v_pk_mul_f32 v[174:175], v[190:191], v[142:143] op_sel_hi:[0,1]
	v_pk_mul_f32 v[176:177], v[190:191], v[144:145] op_sel_hi:[0,1]
	v_pk_mul_f32 v[174:175], v[174:175], v[56:57]
	v_pk_mul_f32 v[176:177], v[176:177], v[58:59]
	v_cvt_pk_bf16_f32 v162, v174, v175
	v_cvt_pk_bf16_f32 v163, v176, v177
	global_store_dwordx2 v181, v[162:163], s[38:39] offset:3072
	v_pk_mul_f32 v[174:175], v[190:191], v[146:147] op_sel_hi:[0,1]
	v_pk_mul_f32 v[176:177], v[190:191], v[148:149] op_sel_hi:[0,1]
	v_pk_mul_f32 v[174:175], v[174:175], v[60:61]
	v_pk_mul_f32 v[176:177], v[176:177], v[62:63]
	v_cvt_pk_bf16_f32 v164, v174, v175
	v_cvt_pk_bf16_f32 v165, v176, v177
	global_store_dwordx2 v181, v[164:165], s[38:39] offset:3584
	s_waitcnt vmcnt(51)
	v_cvt_pk_bf16_f32 v170, v170, v171
	v_cvt_pk_bf16_f32 v171, v172, v173
	global_store_dwordx2 v181, v[170:171], s[40:41]
	s_mov_b32 s30, s10
	s_lshl_b32 s2, s30, 13
	s_add_u32 s36, s18, s2
	s_addc_u32 s37, s19, 0
	s_lshl_b32 s2, s30, 12
	s_add_u32 s38, s16, s2
	s_addc_u32 s39, s17, 0
	s_lshl_b32 s2, s30, 9
	s_add_u32 s40, s22, s2
	s_addc_u32 s41, s23, 0
	s_add_i32 s10, s30, s82
	s_cmpk_gt_i32 s10, 0x7fff
	s_cbranch_scc1 .Lp5b_tail_a
	s_lshl_b32 s2, s10, 13
	s_add_u32 s24, s8, s2
	s_addc_u32 s25, s9, 0
	s_lshl_b32 s2, s10, 12
	s_add_u32 s26, s14, s2
	s_addc_u32 s27, s15, 0
	s_lshl_b32 s2, s10, 2
	s_add_u32 s28, s12, s2
	s_addc_u32 s29, s13, 0
	s_lshl_b32 s2, s10, 10
	s_add_u32 s34, s20, s2
	s_addc_u32 s35, s21, 0
	global_load_dword v168, v167, s[28:29]
	global_load_dwordx4 v[118:121], v166, s[24:25] offset:-4096 nt
	global_load_dwordx2 v[150:151], v181, s[26:27] offset:0 nt
	global_load_dwordx4 v[122:125], v166, s[24:25] offset:-3072 nt
	global_load_dwordx2 v[152:153], v181, s[26:27] offset:512 nt
	global_load_dwordx4 v[126:129], v166, s[24:25] offset:-2048 nt
	global_load_dwordx2 v[154:155], v181, s[26:27] offset:1024 nt
	global_load_dwordx4 v[130:133], v166, s[24:25] offset:-1024 nt
	global_load_dwordx2 v[156:157], v181, s[26:27] offset:1536 nt
	global_load_dwordx4 v[134:137], v166, s[24:25] offset:0 nt
	global_load_dwordx2 v[158:159], v181, s[26:27] offset:2048 nt
	global_load_dwordx4 v[138:141], v166, s[24:25] offset:1024 nt
	global_load_dwordx2 v[160:161], v181, s[26:27] offset:2560 nt
	global_load_dwordx4 v[142:145], v166, s[24:25] offset:2048 nt
	global_load_dwordx2 v[162:163], v181, s[26:27] offset:3072 nt
	global_load_dwordx4 v[146:149], v166, s[24:25] offset:3072 nt
	global_load_dwordx2 v[164:165], v181, s[26:27] offset:3584 nt
	global_load_dwordx4 v[170:173], v166, s[34:35]
	s_waitcnt vmcnt(50)
	v_fmamk_f32 v184, v112, 0x3a000000, v182
	v_rsq_f32_e32 v184, v184
	v_lshlrev_b32_e32 v174, 16, v96
	v_and_b32_e32 v175, 0xffff0000, v96
	v_lshlrev_b32_e32 v176, 16, v97
	v_and_b32_e32 v177, 0xffff0000, v97
	v_pk_mul_f32 v[174:175], v[184:185], v[174:175] op_sel_hi:[0,1]
	v_pk_mul_f32 v[176:177], v[184:185], v[176:177] op_sel_hi:[0,1]
	v_pk_fma_f32 v[64:65], v[0:1], v[174:175], v[64:65]
	v_pk_fma_f32 v[66:67], v[2:3], v[176:177], v[66:67]
	global_store_dwordx4 v166, v[64:67], s[36:37] offset:-4096 nt
	v_pk_mul_f32 v[186:187], v[64:65], v[64:65]
	v_pk_mul_f32 v[188:189], v[66:67], v[66:67]
	s_waitcnt vmcnt(49)
	v_lshlrev_b32_e32 v174, 16, v98
	v_and_b32_e32 v175, 0xffff0000, v98
	v_lshlrev_b32_e32 v176, 16, v99
	v_and_b32_e32 v177, 0xffff0000, v99
	v_pk_mul_f32 v[174:175], v[184:185], v[174:175] op_sel_hi:[0,1]
	v_pk_mul_f32 v[176:177], v[184:185], v[176:177] op_sel_hi:[0,1]
	v_pk_fma_f32 v[68:69], v[4:5], v[174:175], v[68:69]
	v_pk_fma_f32 v[70:71], v[6:7], v[176:177], v[70:71]
	global_store_dwordx4 v166, v[68:71], s[36:37] offset:-3072 nt
	v_pk_fma_f32 v[186:187], v[68:69], v[68:69], v[186:187]
	v_pk_fma_f32 v[188:189], v[70:71], v[70:71], v[188:189]
	s_waitcnt vmcnt(48)
	v_lshlrev_b32_e32 v174, 16, v100
	v_and_b32_e32 v175, 0xffff0000, v100
	v_lshlrev_b32_e32 v176, 16, v101
	v_and_b32_e32 v177, 0xffff0000, v101
	v_pk_mul_f32 v[174:175], v[184:185], v[174:175] op_sel_hi:[0,1]
	v_pk_mul_f32 v[176:177], v[184:185], v[176:177] op_sel_hi:[0,1]
	v_pk_fma_f32 v[72:73], v[8:9], v[174:175], v[72:73]
	v_pk_fma_f32 v[74:75], v[10:11], v[176:177], v[74:75]
	global_store_dwordx4 v166, v[72:75], s[36:37] offset:-2048 nt
	v_pk_fma_f32 v[186:187], v[72:73], v[72:73], v[186:187]
	v_pk_fma_f32 v[188:189], v[74:75], v[74:75], v[188:189]
	s_waitcnt vmcnt(47)
	v_lshlrev_b32_e32 v174, 16, v102
	v_and_b32_e32 v175, 0xffff0000, v102
	v_lshlrev_b32_e32 v176, 16, v103
	v_and_b32_e32 v177, 0xffff0000, v103
	v_pk_mul_f32 v[174:175], v[184:185], v[174:175] op_sel_hi:[0,1]
	v_pk_mul_f32 v[176:177], v[184:185], v[176:177] op_sel_hi:[0,1]
	v_pk_fma_f32 v[76:77], v[12:13], v[174:175], v[76:77]
	v_pk_fma_f32 v[78:79], v[14:15], v[176:177], v[78:79]
	global_store_dwordx4 v166, v[76:79], s[36:37] offset:-1024 nt
	v_pk_fma_f32 v[186:187], v[76:77], v[76:77], v[186:187]
	v_pk_fma_f32 v[188:189], v[78:79], v[78:79], v[188:189]
	s_waitcnt vmcnt(46)
	v_lshlrev_b32_e32 v174, 16, v104
	v_and_b32_e32 v175, 0xffff0000, v104
	v_lshlrev_b32_e32 v176, 16, v105
	v_and_b32_e32 v177, 0xffff0000, v105
	v_pk_mul_f32 v[174:175], v[184:185], v[174:175] op_sel_hi:[0,1]
	v_pk_mul_f32 v[176:177], v[184:185], v[176:177] op_sel_hi:[0,1]
	v_pk_fma_f32 v[80:81], v[16:17], v[174:175], v[80:81]
	v_pk_fma_f32 v[82:83], v[18:19], v[176:177], v[82:83]
	global_store_dwordx4 v166, v[80:83], s[36:37] offset:0 nt
	v_pk_fma_f32 v[186:187], v[80:81], v[80:81], v[186:187]
	v_pk_fma_f32 v[188:189], v[82:83], v[82:83], v[188:189]
	s_waitcnt vmcnt(45)
	v_lshlrev_b32_e32 v174, 16, v106
	v_and_b32_e32 v175, 0xffff0000, v106
	v_lshlrev_b32_e32 v176, 16, v107
	v_and_b32_e32 v177, 0xffff0000, v107
	v_pk_mul_f32 v[174:175], v[184:185], v[174:175] op_sel_hi:[0,1]
	v_pk_mul_f32 v[176:177], v[184:185], v[176:177] op_sel_hi:[0,1]
	v_pk_fma_f32 v[84:85], v[20:21], v[174:175], v[84:85]
	v_pk_fma_f32 v[86:87], v[22:23], v[176:177], v[86:87]
	global_store_dwordx4 v166, v[84:87], s[36:37] offset:1024 nt
	v_pk_fma_f32 v[186:187], v[84:85], v[84:85], v[186:187]
	v_pk_fma_f32 v[188:189], v[86:87], v[86:87], v[188:189]
	s_waitcnt vmcnt(44)
	v_lshlrev_b32_e32 v174, 16, v108
	v_and_b32_e32 v175, 0xffff0000, v108
	v_lshlrev_b32_e32 v176, 16, v109
	v_and_b32_e32 v177, 0xffff0000, v109
	v_pk_mul_f32 v[174:175], v[184:185], v[174:175] op_sel_hi:[0,1]
	v_pk_mul_f32 v[176:177], v[184:185], v[176:177] op_sel_hi:[0,1]
	v_pk_fma_f32 v[88:89], v[24:25], v[174:175], v[88:89]
	v_pk_fma_f32 v[90:91], v[26:27], v[176:177], v[90:91]
	global_store_dwordx4 v166, v[88:91], s[36:37] offset:2048 nt
	v_pk_fma_f32 v[186:187], v[88:89], v[88:89], v[186:187]
	v_pk_fma_f32 v[188:189], v[90:91], v[90:91], v[188:189]
	s_waitcnt vmcnt(43)
	v_lshlrev_b32_e32 v174, 16, v110
	v_and_b32_e32 v175, 0xffff0000, v110
	v_lshlrev_b32_e32 v176, 16, v111
	v_and_b32_e32 v177, 0xffff0000, v111
	v_pk_mul_f32 v[174:175], v[184:185], v[174:175] op_sel_hi:[0,1]
	v_pk_mul_f32 v[176:177], v[184:185], v[176:177] op_sel_hi:[0,1]
	v_pk_fma_f32 v[92:93], v[28:29], v[174:175], v[92:93]
	v_pk_fma_f32 v[94:95], v[30:31], v[176:177], v[94:95]
	global_store_dwordx4 v166, v[92:95], s[36:37] offset:3072 nt
	v_pk_fma_f32 v[186:187], v[92:93], v[92:93], v[186:187]
	v_pk_fma_f32 v[188:189], v[94:95], v[94:95], v[188:189]
	v_add_f32_e32 v186, v186, v187
	v_add_f32_e32 v188, v188, v189
	v_add_f32_e32 v186, v186, v188
	s_nop 1
	v_add_f32_dpp v186, v186, v186 quad_perm:[1,0,3,2] row_mask:0xf bank_mask:0xf
	s_nop 1
	v_add_f32_dpp v186, v186, v186 quad_perm:[2,3,0,1] row_mask:0xf bank_mask:0xf
	s_nop 1
	v_add_f32_dpp v186, v186, v186 row_half_mirror row_mask:0xf bank_mask:0xf
	s_nop 1
	v_add_f32_dpp v186, v186, v186 row_mirror row_mask:0xf bank_mask:0xf
	s_nop 1
	v_readlane_b32 s24, v186, 0
	v_readlane_b32 s25, v186, 16
	v_readlane_b32 s26, v186, 32
	v_readlane_b32 s27, v186, 48
	v_mov_b32_e32 v190, s24
	v_add_f32_e32 v190, s25, v190
	v_add_f32_e32 v190, s26, v190
	v_add_f32_e32 v190, s27, v190
	v_fmamk_f32 v190, v190, 0x3a000000, v182
	v_rsq_f32_e32 v190, v190
	s_nop 0
	v_pk_mul_f32 v[174:175], v[190:191], v[64:65] op_sel_hi:[0,1]
	v_pk_mul_f32 v[176:177], v[190:191], v[66:67] op_sel_hi:[0,1]
	v_pk_mul_f32 v[174:175], v[174:175], v[32:33]
	v_pk_mul_f32 v[176:177], v[176:177], v[34:35]
	v_cvt_pk_bf16_f32 v96, v174, v175
	v_cvt_pk_bf16_f32 v97, v176, v177
	global_store_dwordx2 v181, v[96:97], s[38:39] offset:0
	v_pk_mul_f32 v[174:175], v[190:191], v[68:69] op_sel_hi:[0,1]
	v_pk_mul_f32 v[176:177], v[190:191], v[70:71] op_sel_hi:[0,1]
	v_pk_mul_f32 v[174:175], v[174:175], v[36:37]
	v_pk_mul_f32 v[176:177], v[176:177], v[38:39]
	v_cvt_pk_bf16_f32 v98, v174, v175
	v_cvt_pk_bf16_f32 v99, v176, v177
	global_store_dwordx2 v181, v[98:99], s[38:39] offset:512
	v_pk_mul_f32 v[174:175], v[190:191], v[72:73] op_sel_hi:[0,1]
	v_pk_mul_f32 v[176:177], v[190:191], v[74:75] op_sel_hi:[0,1]
	v_pk_mul_f32 v[174:175], v[174:175], v[40:41]
	v_pk_mul_f32 v[176:177], v[176:177], v[42:43]
	v_cvt_pk_bf16_f32 v100, v174, v175
	v_cvt_pk_bf16_f32 v101, v176, v177
	global_store_dwordx2 v181, v[100:101], s[38:39] offset:1024
	v_pk_mul_f32 v[174:175], v[190:191], v[76:77] op_sel_hi:[0,1]
	v_pk_mul_f32 v[176:177], v[190:191], v[78:79] op_sel_hi:[0,1]
	v_pk_mul_f32 v[174:175], v[174:175], v[44:45]
	v_pk_mul_f32 v[176:177], v[176:177], v[46:47]
	v_cvt_pk_bf16_f32 v102, v174, v175
	v_cvt_pk_bf16_f32 v103, v176, v177
	global_store_dwordx2 v181, v[102:103], s[38:39] offset:1536
	v_pk_mul_f32 v[174:175], v[190:191], v[80:81] op_sel_hi:[0,1]
	v_pk_mul_f32 v[176:177], v[190:191], v[82:83] op_sel_hi:[0,1]
	v_pk_mul_f32 v[174:175], v[174:175], v[48:49]
	v_pk_mul_f32 v[176:177], v[176:177], v[50:51]
	v_cvt_pk_bf16_f32 v104, v174, v175
	v_cvt_pk_bf16_f32 v105, v176, v177
	global_store_dwordx2 v181, v[104:105], s[38:39] offset:2048
	v_pk_mul_f32 v[174:175], v[190:191], v[84:85] op_sel_hi:[0,1]
	v_pk_mul_f32 v[176:177], v[190:191], v[86:87] op_sel_hi:[0,1]
	v_pk_mul_f32 v[174:175], v[174:175], v[52:53]
	v_pk_mul_f32 v[176:177], v[176:177], v[54:55]
	v_cvt_pk_bf16_f32 v106, v174, v175
	v_cvt_pk_bf16_f32 v107, v176, v177
	global_store_dwordx2 v181, v[106:107], s[38:39] offset:2560
	v_pk_mul_f32 v[174:175], v[190:191], v[88:89] op_sel_hi:[0,1]
	v_pk_mul_f32 v[176:177], v[190:191], v[90:91] op_sel_hi:[0,1]
	v_pk_mul_f32 v[174:175], v[174:175], v[56:57]
	v_pk_mul_f32 v[176:177], v[176:177], v[58:59]
	v_cvt_pk_bf16_f32 v108, v174, v175
	v_cvt_pk_bf16_f32 v109, v176, v177
	global_store_dwordx2 v181, v[108:109], s[38:39] offset:3072
	v_pk_mul_f32 v[174:175], v[190:191], v[92:93] op_sel_hi:[0,1]
	v_pk_mul_f32 v[176:177], v[190:191], v[94:95] op_sel_hi:[0,1]
	v_pk_mul_f32 v[174:175], v[174:175], v[60:61]
	v_pk_mul_f32 v[176:177], v[176:177], v[62:63]
	v_cvt_pk_bf16_f32 v110, v174, v175
	v_cvt_pk_bf16_f32 v111, v176, v177
	global_store_dwordx2 v181, v[110:111], s[38:39] offset:3584
	s_waitcnt vmcnt(51)
	v_cvt_pk_bf16_f32 v114, v114, v115
	v_cvt_pk_bf16_f32 v115, v116, v117
	global_store_dwordx2 v181, v[114:115], s[40:41]
	s_mov_b32 s30, s10
	s_branch .Lp5b_loop
.Lp5b_tail_a:
	s_waitcnt vmcnt(32)
	v_fmamk_f32 v184, v112, 0x3a000000, v182
	v_rsq_f32_e32 v184, v184
	v_lshlrev_b32_e32 v174, 16, v96
	v_and_b32_e32 v175, 0xffff0000, v96
	v_lshlrev_b32_e32 v176, 16, v97
	v_and_b32_e32 v177, 0xffff0000, v97
	v_pk_mul_f32 v[174:175], v[184:185], v[174:175] op_sel_hi:[0,1]
	v_pk_mul_f32 v[176:177], v[184:185], v[176:177] op_sel_hi:[0,1]
	v_pk_fma_f32 v[64:65], v[0:1], v[174:175], v[64:65]
	v_pk_fma_f32 v[66:67], v[2:3], v[176:177], v[66:67]
	global_store_dwordx4 v166, v[64:67], s[36:37] offset:-4096 nt
	v_pk_mul_f32 v[186:187], v[64:65], v[64:65]
	v_pk_mul_f32 v[188:189], v[66:67], v[66:67]
	s_waitcnt vmcnt(31)
	v_lshlrev_b32_e32 v174, 16, v98
	v_and_b32_e32 v175, 0xffff0000, v98
	v_lshlrev_b32_e32 v176, 16, v99
	v_and_b32_e32 v177, 0xffff0000, v99
	v_pk_mul_f32 v[174:175], v[184:185], v[174:175] op_sel_hi:[0,1]
	v_pk_mul_f32 v[176:177], v[184:185], v[176:177] op_sel_hi:[0,1]
	v_pk_fma_f32 v[68:69], v[4:5], v[174:175], v[68:69]
	v_pk_fma_f32 v[70:71], v[6:7], v[176:177], v[70:71]
	global_store_dwordx4 v166, v[68:71], s[36:37] offset:-3072 nt
	v_pk_fma_f32 v[186:187], v[68:69], v[68:69], v[186:187]
	v_pk_fma_f32 v[188:189], v[70:71], v[70:71], v[188:189]
	s_waitcnt vmcnt(30)
	v_lshlrev_b32_e32 v174, 16, v100
	v_and_b32_e32 v175, 0xffff0000, v100
	v_lshlrev_b32_e32 v176, 16, v101
	v_and_b32_e32 v177, 0xffff0000, v101
	v_pk_mul_f32 v[174:175], v[184:185], v[174:175] op_sel_hi:[0,1]
	v_pk_mul_f32 v[176:177], v[184:185], v[176:177] op_sel_hi:[0,1]
	v_pk_fma_f32 v[72:73], v[8:9], v[174:175], v[72:73]
	v_pk_fma_f32 v[74:75], v[10:11], v[176:177], v[74:75]
	global_store_dwordx4 v166, v[72:75], s[36:37] offset:-2048 nt
	v_pk_fma_f32 v[186:187], v[72:73], v[72:73], v[186:187]
	v_pk_fma_f32 v[188:189], v[74:75], v[74:75], v[188:189]
	s_waitcnt vmcnt(29)
	v_lshlrev_b32_e32 v174, 16, v102
	v_and_b32_e32 v175, 0xffff0000, v102
	v_lshlrev_b32_e32 v176, 16, v103
	v_and_b32_e32 v177, 0xffff0000, v103
	v_pk_mul_f32 v[174:175], v[184:185], v[174:175] op_sel_hi:[0,1]
	v_pk_mul_f32 v[176:177], v[184:185], v[176:177] op_sel_hi:[0,1]
	v_pk_fma_f32 v[76:77], v[12:13], v[174:175], v[76:77]
	v_pk_fma_f32 v[78:79], v[14:15], v[176:177], v[78:79]
	global_store_dwordx4 v166, v[76:79], s[36:37] offset:-1024 nt
	v_pk_fma_f32 v[186:187], v[76:77], v[76:77], v[186:187]
	v_pk_fma_f32 v[188:189], v[78:79], v[78:79], v[188:189]
	s_waitcnt vmcnt(28)
	v_lshlrev_b32_e32 v174, 16, v104
	v_and_b32_e32 v175, 0xffff0000, v104
	v_lshlrev_b32_e32 v176, 16, v105
	v_and_b32_e32 v177, 0xffff0000, v105
	v_pk_mul_f32 v[174:175], v[184:185], v[174:175] op_sel_hi:[0,1]
	v_pk_mul_f32 v[176:177], v[184:185], v[176:177] op_sel_hi:[0,1]
	v_pk_fma_f32 v[80:81], v[16:17], v[174:175], v[80:81]
	v_pk_fma_f32 v[82:83], v[18:19], v[176:177], v[82:83]
	global_store_dwordx4 v166, v[80:83], s[36:37] offset:0 nt
	v_pk_fma_f32 v[186:187], v[80:81], v[80:81], v[186:187]
	v_pk_fma_f32 v[188:189], v[82:83], v[82:83], v[188:189]
	s_waitcnt vmcnt(27)
	v_lshlrev_b32_e32 v174, 16, v106
	v_and_b32_e32 v175, 0xffff0000, v106
	v_lshlrev_b32_e32 v176, 16, v107
	v_and_b32_e32 v177, 0xffff0000, v107
	v_pk_mul_f32 v[174:175], v[184:185], v[174:175] op_sel_hi:[0,1]
	v_pk_mul_f32 v[176:177], v[184:185], v[176:177] op_sel_hi:[0,1]
	v_pk_fma_f32 v[84:85], v[20:21], v[174:175], v[84:85]
	v_pk_fma_f32 v[86:87], v[22:23], v[176:177], v[86:87]
	global_store_dwordx4 v166, v[84:87], s[36:37] offset:1024 nt
	v_pk_fma_f32 v[186:187], v[84:85], v[84:85], v[186:187]
	v_pk_fma_f32 v[188:189], v[86:87], v[86:87], v[188:189]
	s_waitcnt vmcnt(26)
	v_lshlrev_b32_e32 v174, 16, v108
	v_and_b32_e32 v175, 0xffff0000, v108
	v_lshlrev_b32_e32 v176, 16, v109
	v_and_b32_e32 v177, 0xffff0000, v109
	v_pk_mul_f32 v[174:175], v[184:185], v[174:175] op_sel_hi:[0,1]
	v_pk_mul_f32 v[176:177], v[184:185], v[176:177] op_sel_hi:[0,1]
	v_pk_fma_f32 v[88:89], v[24:25], v[174:175], v[88:89]
	v_pk_fma_f32 v[90:91], v[26:27], v[176:177], v[90:91]
	global_store_dwordx4 v166, v[88:91], s[36:37] offset:2048 nt
	v_pk_fma_f32 v[186:187], v[88:89], v[88:89], v[186:187]
	v_pk_fma_f32 v[188:189], v[90:91], v[90:91], v[188:189]
	s_waitcnt vmcnt(25)
	v_lshlrev_b32_e32 v174, 16, v110
	v_and_b32_e32 v175, 0xffff0000, v110
	v_lshlrev_b32_e32 v176, 16, v111
	v_and_b32_e32 v177, 0xffff0000, v111
	v_pk_mul_f32 v[174:175], v[184:185], v[174:175] op_sel_hi:[0,1]
	v_pk_mul_f32 v[176:177], v[184:185], v[176:177] op_sel_hi:[0,1]
	v_pk_fma_f32 v[92:93], v[28:29], v[174:175], v[92:93]
	v_pk_fma_f32 v[94:95], v[30:31], v[176:177], v[94:95]
	global_store_dwordx4 v166, v[92:95], s[36:37] offset:3072 nt
	v_pk_fma_f32 v[186:187], v[92:93], v[92:93], v[186:187]
	v_pk_fma_f32 v[188:189], v[94:95], v[94:95], v[188:189]
	v_add_f32_e32 v186, v186, v187
	v_add_f32_e32 v188, v188, v189
	v_add_f32_e32 v186, v186, v188
	s_nop 1
	v_add_f32_dpp v186, v186, v186 quad_perm:[1,0,3,2] row_mask:0xf bank_mask:0xf
	s_nop 1
	v_add_f32_dpp v186, v186, v186 quad_perm:[2,3,0,1] row_mask:0xf bank_mask:0xf
	s_nop 1
	v_add_f32_dpp v186, v186, v186 row_half_mirror row_mask:0xf bank_mask:0xf
	s_nop 1
	v_add_f32_dpp v186, v186, v186 row_mirror row_mask:0xf bank_mask:0xf
	s_nop 1
	v_readlane_b32 s24, v186, 0
	v_readlane_b32 s25, v186, 16
	v_readlane_b32 s26, v186, 32
	v_readlane_b32 s27, v186, 48
	v_mov_b32_e32 v190, s24
	v_add_f32_e32 v190, s25, v190
	v_add_f32_e32 v190, s26, v190
	v_add_f32_e32 v190, s27, v190
	v_fmamk_f32 v190, v190, 0x3a000000, v182
	v_rsq_f32_e32 v190, v190
	s_nop 0
	v_pk_mul_f32 v[174:175], v[190:191], v[64:65] op_sel_hi:[0,1]
	v_pk_mul_f32 v[176:177], v[190:191], v[66:67] op_sel_hi:[0,1]
	v_pk_mul_f32 v[174:175], v[174:175], v[32:33]
	v_pk_mul_f32 v[176:177], v[176:177], v[34:35]
	v_cvt_pk_bf16_f32 v96, v174, v175
	v_cvt_pk_bf16_f32 v97, v176, v177
	global_store_dwordx2 v181, v[96:97], s[38:39] offset:0
	v_pk_mul_f32 v[174:175], v[190:191], v[68:69] op_sel_hi:[0,1]
	v_pk_mul_f32 v[176:177], v[190:191], v[70:71] op_sel_hi:[0,1]
	v_pk_mul_f32 v[174:175], v[174:175], v[36:37]
	v_pk_mul_f32 v[176:177], v[176:177], v[38:39]
	v_cvt_pk_bf16_f32 v98, v174, v175
	v_cvt_pk_bf16_f32 v99, v176, v177
	global_store_dwordx2 v181, v[98:99], s[38:39] offset:512
	v_pk_mul_f32 v[174:175], v[190:191], v[72:73] op_sel_hi:[0,1]
	v_pk_mul_f32 v[176:177], v[190:191], v[74:75] op_sel_hi:[0,1]
	v_pk_mul_f32 v[174:175], v[174:175], v[40:41]
	v_pk_mul_f32 v[176:177], v[176:177], v[42:43]
	v_cvt_pk_bf16_f32 v100, v174, v175
	v_cvt_pk_bf16_f32 v101, v176, v177
	global_store_dwordx2 v181, v[100:101], s[38:39] offset:1024
	v_pk_mul_f32 v[174:175], v[190:191], v[76:77] op_sel_hi:[0,1]
	v_pk_mul_f32 v[176:177], v[190:191], v[78:79] op_sel_hi:[0,1]
	v_pk_mul_f32 v[174:175], v[174:175], v[44:45]
	v_pk_mul_f32 v[176:177], v[176:177], v[46:47]
	v_cvt_pk_bf16_f32 v102, v174, v175
	v_cvt_pk_bf16_f32 v103, v176, v177
	global_store_dwordx2 v181, v[102:103], s[38:39] offset:1536
	v_pk_mul_f32 v[174:175], v[190:191], v[80:81] op_sel_hi:[0,1]
	v_pk_mul_f32 v[176:177], v[190:191], v[82:83] op_sel_hi:[0,1]
	v_pk_mul_f32 v[174:175], v[174:175], v[48:49]
	v_pk_mul_f32 v[176:177], v[176:177], v[50:51]
	v_cvt_pk_bf16_f32 v104, v174, v175
	v_cvt_pk_bf16_f32 v105, v176, v177
	global_store_dwordx2 v181, v[104:105], s[38:39] offset:2048
	v_pk_mul_f32 v[174:175], v[190:191], v[84:85] op_sel_hi:[0,1]
	v_pk_mul_f32 v[176:177], v[190:191], v[86:87] op_sel_hi:[0,1]
	v_pk_mul_f32 v[174:175], v[174:175], v[52:53]
	v_pk_mul_f32 v[176:177], v[176:177], v[54:55]
	v_cvt_pk_bf16_f32 v106, v174, v175
	v_cvt_pk_bf16_f32 v107, v176, v177
	global_store_dwordx2 v181, v[106:107], s[38:39] offset:2560
	v_pk_mul_f32 v[174:175], v[190:191], v[88:89] op_sel_hi:[0,1]
	v_pk_mul_f32 v[176:177], v[190:191], v[90:91] op_sel_hi:[0,1]
	v_pk_mul_f32 v[174:175], v[174:175], v[56:57]
	v_pk_mul_f32 v[176:177], v[176:177], v[58:59]
	v_cvt_pk_bf16_f32 v108, v174, v175
	v_cvt_pk_bf16_f32 v109, v176, v177
	global_store_dwordx2 v181, v[108:109], s[38:39] offset:3072
	v_pk_mul_f32 v[174:175], v[190:191], v[92:93] op_sel_hi:[0,1]
	v_pk_mul_f32 v[176:177], v[190:191], v[94:95] op_sel_hi:[0,1]
	v_pk_mul_f32 v[174:175], v[174:175], v[60:61]
	v_pk_mul_f32 v[176:177], v[176:177], v[62:63]
	v_cvt_pk_bf16_f32 v110, v174, v175
	v_cvt_pk_bf16_f32 v111, v176, v177
	global_store_dwordx2 v181, v[110:111], s[38:39] offset:3584
	s_waitcnt vmcnt(33)
	v_cvt_pk_bf16_f32 v114, v114, v115
	v_cvt_pk_bf16_f32 v115, v116, v117
	global_store_dwordx2 v181, v[114:115], s[40:41]
	s_branch .Lp5b_done
.Lp5b_tail_b:
	s_waitcnt vmcnt(32)
	v_fmamk_f32 v184, v168, 0x3a000000, v182
	v_rsq_f32_e32 v184, v184
	v_lshlrev_b32_e32 v174, 16, v150
	v_and_b32_e32 v175, 0xffff0000, v150
	v_lshlrev_b32_e32 v176, 16, v151
	v_and_b32_e32 v177, 0xffff0000, v151
	v_pk_mul_f32 v[174:175], v[184:185], v[174:175] op_sel_hi:[0,1]
	v_pk_mul_f32 v[176:177], v[184:185], v[176:177] op_sel_hi:[0,1]
	v_pk_fma_f32 v[118:119], v[0:1], v[174:175], v[118:119]
	v_pk_fma_f32 v[120:121], v[2:3], v[176:177], v[120:121]
	global_store_dwordx4 v166, v[118:121], s[36:37] offset:-4096 nt
	v_pk_mul_f32 v[186:187], v[118:119], v[118:119]
	v_pk_mul_f32 v[188:189], v[120:121], v[120:121]
	s_waitcnt vmcnt(31)
	v_lshlrev_b32_e32 v174, 16, v152
	v_and_b32_e32 v175, 0xffff0000, v152
	v_lshlrev_b32_e32 v176, 16, v153
	v_and_b32_e32 v177, 0xffff0000, v153
	v_pk_mul_f32 v[174:175], v[184:185], v[174:175] op_sel_hi:[0,1]
	v_pk_mul_f32 v[176:177], v[184:185], v[176:177] op_sel_hi:[0,1]
	v_pk_fma_f32 v[122:123], v[4:5], v[174:175], v[122:123]
	v_pk_fma_f32 v[124:125], v[6:7], v[176:177], v[124:125]
	global_store_dwordx4 v166, v[122:125], s[36:37] offset:-3072 nt
	v_pk_fma_f32 v[186:187], v[122:123], v[122:123], v[186:187]
	v_pk_fma_f32 v[188:189], v[124:125], v[124:125], v[188:189]
	s_waitcnt vmcnt(30)
	v_lshlrev_b32_e32 v174, 16, v154
	v_and_b32_e32 v175, 0xffff0000, v154
	v_lshlrev_b32_e32 v176, 16, v155
	v_and_b32_e32 v177, 0xffff0000, v155
	v_pk_mul_f32 v[174:175], v[184:185], v[174:175] op_sel_hi:[0,1]
	v_pk_mul_f32 v[176:177], v[184:185], v[176:177] op_sel_hi:[0,1]
	v_pk_fma_f32 v[126:127], v[8:9], v[174:175], v[126:127]
	v_pk_fma_f32 v[128:129], v[10:11], v[176:177], v[128:129]
	global_store_dwordx4 v166, v[126:129], s[36:37] offset:-2048 nt
	v_pk_fma_f32 v[186:187], v[126:127], v[126:127], v[186:187]
	v_pk_fma_f32 v[188:189], v[128:129], v[128:129], v[188:189]
	s_waitcnt vmcnt(29)
	v_lshlrev_b32_e32 v174, 16, v156
	v_and_b32_e32 v175, 0xffff0000, v156
	v_lshlrev_b32_e32 v176, 16, v157
	v_and_b32_e32 v177, 0xffff0000, v157
	v_pk_mul_f32 v[174:175], v[184:185], v[174:175] op_sel_hi:[0,1]
	v_pk_mul_f32 v[176:177], v[184:185], v[176:177] op_sel_hi:[0,1]
	v_pk_fma_f32 v[130:131], v[12:13], v[174:175], v[130:131]
	v_pk_fma_f32 v[132:133], v[14:15], v[176:177], v[132:133]
	global_store_dwordx4 v166, v[130:133], s[36:37] offset:-1024 nt
	v_pk_fma_f32 v[186:187], v[130:131], v[130:131], v[186:187]
	v_pk_fma_f32 v[188:189], v[132:133], v[132:133], v[188:189]
	s_waitcnt vmcnt(28)
	v_lshlrev_b32_e32 v174, 16, v158
	v_and_b32_e32 v175, 0xffff0000, v158
	v_lshlrev_b32_e32 v176, 16, v159
	v_and_b32_e32 v177, 0xffff0000, v159
	v_pk_mul_f32 v[174:175], v[184:185], v[174:175] op_sel_hi:[0,1]
	v_pk_mul_f32 v[176:177], v[184:185], v[176:177] op_sel_hi:[0,1]
	v_pk_fma_f32 v[134:135], v[16:17], v[174:175], v[134:135]
	v_pk_fma_f32 v[136:137], v[18:19], v[176:177], v[136:137]
	global_store_dwordx4 v166, v[134:137], s[36:37] offset:0 nt
	v_pk_fma_f32 v[186:187], v[134:135], v[134:135], v[186:187]
	v_pk_fma_f32 v[188:189], v[136:137], v[136:137], v[188:189]
	s_waitcnt vmcnt(27)
	v_lshlrev_b32_e32 v174, 16, v160
	v_and_b32_e32 v175, 0xffff0000, v160
	v_lshlrev_b32_e32 v176, 16, v161
	v_and_b32_e32 v177, 0xffff0000, v161
	v_pk_mul_f32 v[174:175], v[184:185], v[174:175] op_sel_hi:[0,1]
	v_pk_mul_f32 v[176:177], v[184:185], v[176:177] op_sel_hi:[0,1]
	v_pk_fma_f32 v[138:139], v[20:21], v[174:175], v[138:139]
	v_pk_fma_f32 v[140:141], v[22:23], v[176:177], v[140:141]
	global_store_dwordx4 v166, v[138:141], s[36:37] offset:1024 nt
	v_pk_fma_f32 v[186:187], v[138:139], v[138:139], v[186:187]
	v_pk_fma_f32 v[188:189], v[140:141], v[140:141], v[188:189]
	s_waitcnt vmcnt(26)
	v_lshlrev_b32_e32 v174, 16, v162
	v_and_b32_e32 v175, 0xffff0000, v162
	v_lshlrev_b32_e32 v176, 16, v163
	v_and_b32_e32 v177, 0xffff0000, v163
	v_pk_mul_f32 v[174:175], v[184:185], v[174:175] op_sel_hi:[0,1]
	v_pk_mul_f32 v[176:177], v[184:185], v[176:177] op_sel_hi:[0,1]
	v_pk_fma_f32 v[142:143], v[24:25], v[174:175], v[142:143]
	v_pk_fma_f32 v[144:145], v[26:27], v[176:177], v[144:145]
	global_store_dwordx4 v166, v[142:145], s[36:37] offset:2048 nt
	v_pk_fma_f32 v[186:187], v[142:143], v[142:143], v[186:187]
	v_pk_fma_f32 v[188:189], v[144:145], v[144:145], v[188:189]
	s_waitcnt vmcnt(25)
	v_lshlrev_b32_e32 v174, 16, v164
	v_and_b32_e32 v175, 0xffff0000, v164
	v_lshlrev_b32_e32 v176, 16, v165
	v_and_b32_e32 v177, 0xffff0000, v165
	v_pk_mul_f32 v[174:175], v[184:185], v[174:175] op_sel_hi:[0,1]
	v_pk_mul_f32 v[176:177], v[184:185], v[176:177] op_sel_hi:[0,1]
	v_pk_fma_f32 v[146:147], v[28:29], v[174:175], v[146:147]
	v_pk_fma_f32 v[148:149], v[30:31], v[176:177], v[148:149]
	global_store_dwordx4 v166, v[146:149], s[36:37] offset:3072 nt
	v_pk_fma_f32 v[186:187], v[146:147], v[146:147], v[186:187]
	v_pk_fma_f32 v[188:189], v[148:149], v[148:149], v[188:189]
	v_add_f32_e32 v186, v186, v187
	v_add_f32_e32 v188, v188, v189
	v_add_f32_e32 v186, v186, v188
	s_nop 1
	v_add_f32_dpp v186, v186, v186 quad_perm:[1,0,3,2] row_mask:0xf bank_mask:0xf
	s_nop 1
	v_add_f32_dpp v186, v186, v186 quad_perm:[2,3,0,1] row_mask:0xf bank_mask:0xf
	s_nop 1
	v_add_f32_dpp v186, v186, v186 row_half_mirror row_mask:0xf bank_mask:0xf
	s_nop 1
	v_add_f32_dpp v186, v186, v186 row_mirror row_mask:0xf bank_mask:0xf
	s_nop 1
	v_readlane_b32 s24, v186, 0
	v_readlane_b32 s25, v186, 16
	v_readlane_b32 s26, v186, 32
	v_readlane_b32 s27, v186, 48
	v_mov_b32_e32 v190, s24
	v_add_f32_e32 v190, s25, v190
	v_add_f32_e32 v190, s26, v190
	v_add_f32_e32 v190, s27, v190
	v_fmamk_f32 v190, v190, 0x3a000000, v182
	v_rsq_f32_e32 v190, v190
	s_nop 0
	v_pk_mul_f32 v[174:175], v[190:191], v[118:119] op_sel_hi:[0,1]
	v_pk_mul_f32 v[176:177], v[190:191], v[120:121] op_sel_hi:[0,1]
	v_pk_mul_f32 v[174:175], v[174:175], v[32:33]
	v_pk_mul_f32 v[176:177], v[176:177], v[34:35]
	v_cvt_pk_bf16_f32 v150, v174, v175
	v_cvt_pk_bf16_f32 v151, v176, v177
	global_store_dwordx2 v181, v[150:151], s[38:39] offset:0
	v_pk_mul_f32 v[174:175], v[190:191], v[122:123] op_sel_hi:[0,1]
	v_pk_mul_f32 v[176:177], v[190:191], v[124:125] op_sel_hi:[0,1]
	v_pk_mul_f32 v[174:175], v[174:175], v[36:37]
	v_pk_mul_f32 v[176:177], v[176:177], v[38:39]
	v_cvt_pk_bf16_f32 v152, v174, v175
	v_cvt_pk_bf16_f32 v153, v176, v177
	global_store_dwordx2 v181, v[152:153], s[38:39] offset:512
	v_pk_mul_f32 v[174:175], v[190:191], v[126:127] op_sel_hi:[0,1]
	v_pk_mul_f32 v[176:177], v[190:191], v[128:129] op_sel_hi:[0,1]
	v_pk_mul_f32 v[174:175], v[174:175], v[40:41]
	v_pk_mul_f32 v[176:177], v[176:177], v[42:43]
	v_cvt_pk_bf16_f32 v154, v174, v175
	v_cvt_pk_bf16_f32 v155, v176, v177
	global_store_dwordx2 v181, v[154:155], s[38:39] offset:1024
	v_pk_mul_f32 v[174:175], v[190:191], v[130:131] op_sel_hi:[0,1]
	v_pk_mul_f32 v[176:177], v[190:191], v[132:133] op_sel_hi:[0,1]
	v_pk_mul_f32 v[174:175], v[174:175], v[44:45]
	v_pk_mul_f32 v[176:177], v[176:177], v[46:47]
	v_cvt_pk_bf16_f32 v156, v174, v175
	v_cvt_pk_bf16_f32 v157, v176, v177
	global_store_dwordx2 v181, v[156:157], s[38:39] offset:1536
	v_pk_mul_f32 v[174:175], v[190:191], v[134:135] op_sel_hi:[0,1]
	v_pk_mul_f32 v[176:177], v[190:191], v[136:137] op_sel_hi:[0,1]
	v_pk_mul_f32 v[174:175], v[174:175], v[48:49]
	v_pk_mul_f32 v[176:177], v[176:177], v[50:51]
	v_cvt_pk_bf16_f32 v158, v174, v175
	v_cvt_pk_bf16_f32 v159, v176, v177
	global_store_dwordx2 v181, v[158:159], s[38:39] offset:2048
	v_pk_mul_f32 v[174:175], v[190:191], v[138:139] op_sel_hi:[0,1]
	v_pk_mul_f32 v[176:177], v[190:191], v[140:141] op_sel_hi:[0,1]
	v_pk_mul_f32 v[174:175], v[174:175], v[52:53]
	v_pk_mul_f32 v[176:177], v[176:177], v[54:55]
	v_cvt_pk_bf16_f32 v160, v174, v175
	v_cvt_pk_bf16_f32 v161, v176, v177
	global_store_dwordx2 v181, v[160:161], s[38:39] offset:2560
	v_pk_mul_f32 v[174:175], v[190:191], v[142:143] op_sel_hi:[0,1]
	v_pk_mul_f32 v[176:177], v[190:191], v[144:145] op_sel_hi:[0,1]
	v_pk_mul_f32 v[174:175], v[174:175], v[56:57]
	v_pk_mul_f32 v[176:177], v[176:177], v[58:59]
	v_cvt_pk_bf16_f32 v162, v174, v175
	v_cvt_pk_bf16_f32 v163, v176, v177
	global_store_dwordx2 v181, v[162:163], s[38:39] offset:3072
	v_pk_mul_f32 v[174:175], v[190:191], v[146:147] op_sel_hi:[0,1]
	v_pk_mul_f32 v[176:177], v[190:191], v[148:149] op_sel_hi:[0,1]
	v_pk_mul_f32 v[174:175], v[174:175], v[60:61]
	v_pk_mul_f32 v[176:177], v[176:177], v[62:63]
	v_cvt_pk_bf16_f32 v164, v174, v175
	v_cvt_pk_bf16_f32 v165, v176, v177
	global_store_dwordx2 v181, v[164:165], s[38:39] offset:3584
	s_waitcnt vmcnt(33)
	v_cvt_pk_bf16_f32 v170, v170, v171
	v_cvt_pk_bf16_f32 v171, v172, v173
	global_store_dwordx2 v181, v[170:171], s[40:41]
